# v025 + accumulator zeroing with v_mov_b64 (64 instead of 128 moves per unit)
# baseline (speedup 1.0000x reference)
.LBB0_248:
	s_ashr_i32 s25, s24, 31
	s_lshl_b64 s[28:29], s[24:25], 19
	s_add_u32 s28, s43, s28
	s_addc_u32 s29, s44, s29
	s_and_b64 s[0:1], s[0:1], exec
	s_cselect_b32 s5, s29, s31
	s_cselect_b32 s25, s28, s30
	s_cmp_lg_u32 s34, 0
	s_cselect_b64 s[0:1], -1, 0
	s_add_u32 s78, s30, 0x100
	v_mov_b32_e32 v66, 0
	s_addc_u32 s79, s31, 0
	s_mov_b32 s80, -2
	s_mov_b64 s[30:31], 0
	v_mov_b64_e32 v[66:67], 0
	v_mov_b64_e32 v[68:69], 0
	v_mov_b64_e32 v[70:71], 0
	v_mov_b64_e32 v[72:73], 0
	v_mov_b64_e32 v[74:75], 0
	v_mov_b64_e32 v[76:77], 0
	v_mov_b64_e32 v[78:79], 0
	v_mov_b64_e32 v[80:81], 0
	v_mov_b64_e32 v[82:83], 0
	v_mov_b64_e32 v[84:85], 0
	v_mov_b64_e32 v[86:87], 0
	v_mov_b64_e32 v[88:89], 0
	v_mov_b64_e32 v[90:91], 0
	v_mov_b64_e32 v[92:93], 0
	v_mov_b64_e32 v[94:95], 0
	v_mov_b64_e32 v[96:97], 0
	v_mov_b64_e32 v[98:99], 0
	v_mov_b64_e32 v[100:101], 0
	v_mov_b64_e32 v[102:103], 0
	v_mov_b64_e32 v[104:105], 0
	v_mov_b64_e32 v[106:107], 0
	v_mov_b64_e32 v[108:109], 0
	v_mov_b64_e32 v[110:111], 0
	v_mov_b64_e32 v[112:113], 0
	v_mov_b64_e32 v[114:115], 0
	v_mov_b64_e32 v[116:117], 0
	v_mov_b64_e32 v[118:119], 0
	v_mov_b64_e32 v[120:121], 0
	v_mov_b64_e32 v[122:123], 0
	v_mov_b64_e32 v[124:125], 0
	v_mov_b64_e32 v[126:127], 0
	v_mov_b64_e32 v[128:129], 0
	v_mov_b64_e32 v[130:131], 0
	v_mov_b64_e32 v[132:133], 0
	v_mov_b64_e32 v[134:135], 0
	v_mov_b64_e32 v[136:137], 0
	v_mov_b64_e32 v[138:139], 0
	v_mov_b64_e32 v[140:141], 0
	v_mov_b64_e32 v[142:143], 0
	v_mov_b64_e32 v[144:145], 0
	v_mov_b64_e32 v[146:147], 0
	v_mov_b64_e32 v[148:149], 0
	v_mov_b64_e32 v[150:151], 0
	v_mov_b64_e32 v[152:153], 0
	v_mov_b64_e32 v[154:155], 0
	v_mov_b64_e32 v[156:157], 0
	v_mov_b64_e32 v[158:159], 0
	v_mov_b64_e32 v[160:161], 0
	v_mov_b64_e32 v[162:163], 0
	v_mov_b64_e32 v[164:165], 0
	v_mov_b64_e32 v[166:167], 0
	v_mov_b64_e32 v[168:169], 0
	v_mov_b64_e32 v[170:171], 0
	v_mov_b64_e32 v[172:173], 0
	v_mov_b64_e32 v[174:175], 0
	v_mov_b64_e32 v[176:177], 0
	v_mov_b64_e32 v[178:179], 0
	v_mov_b64_e32 v[180:181], 0
	v_mov_b64_e32 v[182:183], 0
	v_mov_b64_e32 v[184:185], 0
	v_mov_b64_e32 v[186:187], 0
	v_mov_b64_e32 v[188:189], 0
	v_mov_b64_e32 v[190:191], 0
	v_mov_b64_e32 v[192:193], 0
	v_lshl_add_u64 v[218:219], s[6:7], 0, v[210:211]
	v_lshl_add_u64 v[220:221], s[6:7], 0, v[212:213]
	s_branch .LBB0_251

.LBB0_883:
	s_lshl_b32 s24, s62, 11
	s_lshl_b32 s25, s61, 8
	s_add_i32 s24, s25, s24
	s_ashr_i32 s25, s24, 31
	s_lshl_b64 s[24:25], s[24:25], 11
	s_add_u32 s24, s34, s24
	s_addc_u32 s25, s35, s25
	s_and_b64 s[0:1], s[0:1], exec
	s_cselect_b32 s66, s25, s7
	s_cselect_b32 s67, s24, s6
	s_cmp_lg_u32 s26, 0
	s_cselect_b64 s[0:1], -1, 0
	s_add_u32 s68, s6, 0x100
	v_mov_b32_e32 v66, 0
	s_addc_u32 s69, s7, 0
	v_lshl_add_u64 v[210:211], s[4:5], 0, v[202:203]
	v_lshl_add_u64 v[212:213], s[4:5], 0, v[204:205]
	s_mov_b32 s70, -2
	s_mov_b64 s[6:7], 0
	v_mov_b64_e32 v[66:67], 0
	v_mov_b64_e32 v[68:69], 0
	v_mov_b64_e32 v[70:71], 0
	v_mov_b64_e32 v[72:73], 0
	v_mov_b64_e32 v[74:75], 0
	v_mov_b64_e32 v[76:77], 0
	v_mov_b64_e32 v[78:79], 0
	v_mov_b64_e32 v[80:81], 0
	v_mov_b64_e32 v[82:83], 0
	v_mov_b64_e32 v[84:85], 0
	v_mov_b64_e32 v[86:87], 0
	v_mov_b64_e32 v[88:89], 0
	v_mov_b64_e32 v[90:91], 0
	v_mov_b64_e32 v[92:93], 0
	v_mov_b64_e32 v[94:95], 0
	v_mov_b64_e32 v[96:97], 0
	v_mov_b64_e32 v[98:99], 0
	v_mov_b64_e32 v[100:101], 0
	v_mov_b64_e32 v[102:103], 0
	v_mov_b64_e32 v[104:105], 0
	v_mov_b64_e32 v[106:107], 0
	v_mov_b64_e32 v[108:109], 0
	v_mov_b64_e32 v[110:111], 0
	v_mov_b64_e32 v[112:113], 0
	v_mov_b64_e32 v[114:115], 0
	v_mov_b64_e32 v[116:117], 0
	v_mov_b64_e32 v[118:119], 0
	v_mov_b64_e32 v[120:121], 0
	v_mov_b64_e32 v[122:123], 0
	v_mov_b64_e32 v[124:125], 0
	v_mov_b64_e32 v[126:127], 0
	v_mov_b64_e32 v[128:129], 0
	v_mov_b64_e32 v[130:131], 0
	v_mov_b64_e32 v[132:133], 0
	v_mov_b64_e32 v[134:135], 0
	v_mov_b64_e32 v[136:137], 0
	v_mov_b64_e32 v[138:139], 0
	v_mov_b64_e32 v[140:141], 0
	v_mov_b64_e32 v[142:143], 0
	v_mov_b64_e32 v[144:145], 0
	v_mov_b64_e32 v[146:147], 0
	v_mov_b64_e32 v[148:149], 0
	v_mov_b64_e32 v[150:151], 0
	v_mov_b64_e32 v[152:153], 0
	v_mov_b64_e32 v[154:155], 0
	v_mov_b64_e32 v[156:157], 0
	v_mov_b64_e32 v[158:159], 0
	v_mov_b64_e32 v[160:161], 0
	v_mov_b64_e32 v[162:163], 0
	v_mov_b64_e32 v[164:165], 0
	v_mov_b64_e32 v[166:167], 0
	v_mov_b64_e32 v[168:169], 0
	v_mov_b64_e32 v[170:171], 0
	v_mov_b64_e32 v[172:173], 0
	v_mov_b64_e32 v[174:175], 0
	v_mov_b64_e32 v[176:177], 0
	v_mov_b64_e32 v[178:179], 0
	v_mov_b64_e32 v[180:181], 0
	v_mov_b64_e32 v[182:183], 0
	v_mov_b64_e32 v[184:185], 0
	v_mov_b64_e32 v[186:187], 0
	v_mov_b64_e32 v[188:189], 0
	v_mov_b64_e32 v[190:191], 0
	v_mov_b64_e32 v[192:193], 0
	s_branch .LBB0_886

.LBB0_1060:
	s_ashr_i32 s21, s20, 31
	s_lshl_b64 s[24:25], s[20:21], 19
	s_add_u32 s24, s45, s24
	s_addc_u32 s25, s46, s25
	s_and_b64 s[26:27], s[2:3], exec
	s_cselect_b32 s21, s25, s31
	s_cselect_b32 s73, s24, s30
	s_ashr_i32 s23, s22, 31
	s_lshl_b64 s[26:27], s[22:23], 19
	s_add_u32 s26, s47, s26
	s_addc_u32 s27, s48, s27
	s_and_b64 s[38:39], s[2:3], exec
	s_cselect_b32 s23, s27, s37
	s_cselect_b32 s74, s26, s36
	s_cmp_lg_u32 s34, 0
	s_cselect_b64 s[34:35], -1, 0
	s_add_u32 s75, s36, 0x100
	v_mov_b32_e32 v66, 0
	s_addc_u32 s76, s37, 0
	v_lshl_add_u64 v[210:211], s[30:31], 0, v[202:203]
	v_lshl_add_u64 v[212:213], s[30:31], 0, v[204:205]
	s_mov_b32 s77, -2
	s_mov_b64 s[36:37], 0
	v_mov_b64_e32 v[66:67], 0
	v_mov_b64_e32 v[68:69], 0
	v_mov_b64_e32 v[70:71], 0
	v_mov_b64_e32 v[72:73], 0
	v_mov_b64_e32 v[74:75], 0
	v_mov_b64_e32 v[76:77], 0
	v_mov_b64_e32 v[78:79], 0
	v_mov_b64_e32 v[80:81], 0
	v_mov_b64_e32 v[82:83], 0
	v_mov_b64_e32 v[84:85], 0
	v_mov_b64_e32 v[86:87], 0
	v_mov_b64_e32 v[88:89], 0
	v_mov_b64_e32 v[90:91], 0
	v_mov_b64_e32 v[92:93], 0
	v_mov_b64_e32 v[94:95], 0
	v_mov_b64_e32 v[96:97], 0
	v_mov_b64_e32 v[98:99], 0
	v_mov_b64_e32 v[100:101], 0
	v_mov_b64_e32 v[102:103], 0
	v_mov_b64_e32 v[104:105], 0
	v_mov_b64_e32 v[106:107], 0
	v_mov_b64_e32 v[108:109], 0
	v_mov_b64_e32 v[110:111], 0
	v_mov_b64_e32 v[112:113], 0
	v_mov_b64_e32 v[114:115], 0
	v_mov_b64_e32 v[116:117], 0
	v_mov_b64_e32 v[118:119], 0
	v_mov_b64_e32 v[120:121], 0
	v_mov_b64_e32 v[122:123], 0
	v_mov_b64_e32 v[124:125], 0
	v_mov_b64_e32 v[126:127], 0
	v_mov_b64_e32 v[128:129], 0
	v_mov_b64_e32 v[130:131], 0
	v_mov_b64_e32 v[132:133], 0
	v_mov_b64_e32 v[134:135], 0
	v_mov_b64_e32 v[136:137], 0
	v_mov_b64_e32 v[138:139], 0
	v_mov_b64_e32 v[140:141], 0
	v_mov_b64_e32 v[142:143], 0
	v_mov_b64_e32 v[144:145], 0
	v_mov_b64_e32 v[146:147], 0
	v_mov_b64_e32 v[148:149], 0
	v_mov_b64_e32 v[150:151], 0
	v_mov_b64_e32 v[152:153], 0
	v_mov_b64_e32 v[154:155], 0
	v_mov_b64_e32 v[156:157], 0
	v_mov_b64_e32 v[158:159], 0
	v_mov_b64_e32 v[160:161], 0
	v_mov_b64_e32 v[162:163], 0
	v_mov_b64_e32 v[164:165], 0
	v_mov_b64_e32 v[166:167], 0
	v_mov_b64_e32 v[168:169], 0
	v_mov_b64_e32 v[170:171], 0
	v_mov_b64_e32 v[172:173], 0
	v_mov_b64_e32 v[174:175], 0
	v_mov_b64_e32 v[176:177], 0
	v_mov_b64_e32 v[178:179], 0
	v_mov_b64_e32 v[180:181], 0
	v_mov_b64_e32 v[182:183], 0
	v_mov_b64_e32 v[184:185], 0
	v_mov_b64_e32 v[186:187], 0
	v_mov_b64_e32 v[188:189], 0
	v_mov_b64_e32 v[190:191], 0
	v_mov_b64_e32 v[192:193], 0
	s_branch .LBB0_1063

.LBB0_1223:
	s_ashr_i32 s35, s34, 31
	s_lshl_b64 s[38:39], s[34:35], 20
	s_add_u32 s38, s59, s38
	s_addc_u32 s39, s60, s39
	s_and_b64 s[40:41], s[14:15], exec
	s_cselect_b32 s35, s39, s47
	s_cselect_b32 s43, s38, s46
	s_ashr_i32 s37, s36, 31
	s_lshl_b64 s[40:41], s[36:37], 20
	s_add_u32 s40, s61, s40
	s_addc_u32 s41, s62, s41
	s_and_b64 s[52:53], s[14:15], exec
	s_cselect_b32 s37, s41, s51
	s_cselect_b32 s45, s40, s50
	s_cmp_lg_u32 s48, 0
	s_cselect_b64 s[48:49], -1, 0
	s_add_u32 s91, s50, 0x100
	v_mov_b32_e32 v2, 0
	s_addc_u32 s92, s51, 0
	v_lshl_add_u64 v[216:217], s[46:47], 0, v[208:209]
	v_lshl_add_u64 v[218:219], s[46:47], 0, v[210:211]
	s_mov_b32 s93, -2
	s_mov_b64 s[50:51], 0
	v_mov_b64_e32 v[2:3], 0
	v_mov_b64_e32 v[4:5], 0
	v_mov_b64_e32 v[6:7], 0
	v_mov_b64_e32 v[8:9], 0
	v_mov_b64_e32 v[10:11], 0
	v_mov_b64_e32 v[12:13], 0
	v_mov_b64_e32 v[14:15], 0
	v_mov_b64_e32 v[16:17], 0
	v_mov_b64_e32 v[18:19], 0
	v_mov_b64_e32 v[20:21], 0
	v_mov_b64_e32 v[22:23], 0
	v_mov_b64_e32 v[24:25], 0
	v_mov_b64_e32 v[26:27], 0
	v_mov_b64_e32 v[28:29], 0
	v_mov_b64_e32 v[30:31], 0
	v_mov_b64_e32 v[32:33], 0
	v_mov_b64_e32 v[34:35], 0
	v_mov_b64_e32 v[36:37], 0
	v_mov_b64_e32 v[38:39], 0
	v_mov_b64_e32 v[40:41], 0
	v_mov_b64_e32 v[42:43], 0
	v_mov_b64_e32 v[44:45], 0
	v_mov_b64_e32 v[46:47], 0
	v_mov_b64_e32 v[48:49], 0
	v_mov_b64_e32 v[50:51], 0
	v_mov_b64_e32 v[52:53], 0
	v_mov_b64_e32 v[54:55], 0
	v_mov_b64_e32 v[56:57], 0
	v_mov_b64_e32 v[58:59], 0
	v_mov_b64_e32 v[60:61], 0
	v_mov_b64_e32 v[62:63], 0
	v_mov_b64_e32 v[64:65], 0
	v_mov_b64_e32 v[98:99], 0
	v_mov_b64_e32 v[100:101], 0
	v_mov_b64_e32 v[102:103], 0
	v_mov_b64_e32 v[104:105], 0
	v_mov_b64_e32 v[106:107], 0
	v_mov_b64_e32 v[108:109], 0
	v_mov_b64_e32 v[110:111], 0
	v_mov_b64_e32 v[112:113], 0
	v_mov_b64_e32 v[114:115], 0
	v_mov_b64_e32 v[116:117], 0
	v_mov_b64_e32 v[118:119], 0
	v_mov_b64_e32 v[120:121], 0
	v_mov_b64_e32 v[122:123], 0
	v_mov_b64_e32 v[124:125], 0
	v_mov_b64_e32 v[126:127], 0
	v_mov_b64_e32 v[128:129], 0
	v_mov_b64_e32 v[130:131], 0
	v_mov_b64_e32 v[132:133], 0
	v_mov_b64_e32 v[134:135], 0
	v_mov_b64_e32 v[136:137], 0
	v_mov_b64_e32 v[138:139], 0
	v_mov_b64_e32 v[140:141], 0
	v_mov_b64_e32 v[142:143], 0
	v_mov_b64_e32 v[144:145], 0
	v_mov_b64_e32 v[146:147], 0
	v_mov_b64_e32 v[148:149], 0
	v_mov_b64_e32 v[150:151], 0
	v_mov_b64_e32 v[152:153], 0
	v_mov_b64_e32 v[154:155], 0
	v_mov_b64_e32 v[156:157], 0
	v_mov_b64_e32 v[158:159], 0
	v_mov_b64_e32 v[160:161], 0
	s_branch .LBB0_1226

.LBB0_1395:
	s_cmp_lg_u32 s24, 0
	s_cselect_b64 s[24:25], -1, 0
	s_add_u32 s70, s26, 0x100
	v_mov_b32_e32 v2, 0
	s_addc_u32 s71, s27, 0
	v_lshl_add_u64 v[210:211], s[22:23], 0, v[202:203]
	v_lshl_add_u64 v[212:213], s[22:23], 0, v[204:205]
	s_mov_b32 s72, -2
	s_mov_b64 s[26:27], 0
	v_mov_b64_e32 v[2:3], 0
	v_mov_b64_e32 v[4:5], 0
	v_mov_b64_e32 v[6:7], 0
	v_mov_b64_e32 v[8:9], 0
	v_mov_b64_e32 v[10:11], 0
	v_mov_b64_e32 v[12:13], 0
	v_mov_b64_e32 v[14:15], 0
	v_mov_b64_e32 v[16:17], 0
	v_mov_b64_e32 v[18:19], 0
	v_mov_b64_e32 v[20:21], 0
	v_mov_b64_e32 v[22:23], 0
	v_mov_b64_e32 v[24:25], 0
	v_mov_b64_e32 v[26:27], 0
	v_mov_b64_e32 v[28:29], 0
	v_mov_b64_e32 v[30:31], 0
	v_mov_b64_e32 v[32:33], 0
	v_mov_b64_e32 v[34:35], 0
	v_mov_b64_e32 v[36:37], 0
	v_mov_b64_e32 v[38:39], 0
	v_mov_b64_e32 v[40:41], 0
	v_mov_b64_e32 v[42:43], 0
	v_mov_b64_e32 v[44:45], 0
	v_mov_b64_e32 v[46:47], 0
	v_mov_b64_e32 v[48:49], 0
	v_mov_b64_e32 v[50:51], 0
	v_mov_b64_e32 v[52:53], 0
	v_mov_b64_e32 v[54:55], 0
	v_mov_b64_e32 v[56:57], 0
	v_mov_b64_e32 v[58:59], 0
	v_mov_b64_e32 v[60:61], 0
	v_mov_b64_e32 v[62:63], 0
	v_mov_b64_e32 v[64:65], 0
	v_mov_b64_e32 v[66:67], 0
	v_mov_b64_e32 v[68:69], 0
	v_mov_b64_e32 v[70:71], 0
	v_mov_b64_e32 v[72:73], 0
	v_mov_b64_e32 v[74:75], 0
	v_mov_b64_e32 v[76:77], 0
	v_mov_b64_e32 v[78:79], 0
	v_mov_b64_e32 v[80:81], 0
	v_mov_b64_e32 v[82:83], 0
	v_mov_b64_e32 v[84:85], 0
	v_mov_b64_e32 v[86:87], 0
	v_mov_b64_e32 v[88:89], 0
	v_mov_b64_e32 v[90:91], 0
	v_mov_b64_e32 v[92:93], 0
	v_mov_b64_e32 v[94:95], 0
	v_mov_b64_e32 v[96:97], 0
	v_mov_b64_e32 v[98:99], 0
	v_mov_b64_e32 v[100:101], 0
	v_mov_b64_e32 v[102:103], 0
	v_mov_b64_e32 v[104:105], 0
	v_mov_b64_e32 v[106:107], 0
	v_mov_b64_e32 v[108:109], 0
	v_mov_b64_e32 v[110:111], 0
	v_mov_b64_e32 v[112:113], 0
	v_mov_b64_e32 v[114:115], 0
	v_mov_b64_e32 v[116:117], 0
	v_mov_b64_e32 v[118:119], 0
	v_mov_b64_e32 v[120:121], 0
	v_mov_b64_e32 v[122:123], 0
	v_mov_b64_e32 v[124:125], 0
	v_mov_b64_e32 v[126:127], 0
	v_mov_b64_e32 v[128:129], 0
	s_branch .LBB0_1398

.LBB0_1588:
	s_ashr_i32 s25, s24, 31
	s_lshl_b64 s[28:29], s[24:25], 19
	s_add_u32 s28, s43, s28
	s_addc_u32 s29, s44, s29
	s_and_b64 s[0:1], s[0:1], exec
	s_cselect_b32 s5, s29, s31
	s_cselect_b32 s25, s28, s30
	s_cmp_lg_u32 s34, 0
	s_cselect_b64 s[0:1], -1, 0
	s_add_u32 s78, s30, 0x100
	v_mov_b32_e32 v66, 0
	s_addc_u32 s79, s31, 0
	v_lshl_add_u64 v[218:219], s[6:7], 0, v[210:211]
	v_lshl_add_u64 v[220:221], s[6:7], 0, v[212:213]
	s_mov_b32 s80, -2
	s_mov_b64 s[30:31], 0
	v_mov_b64_e32 v[66:67], 0
	v_mov_b64_e32 v[68:69], 0
	v_mov_b64_e32 v[70:71], 0
	v_mov_b64_e32 v[72:73], 0
	v_mov_b64_e32 v[74:75], 0
	v_mov_b64_e32 v[76:77], 0
	v_mov_b64_e32 v[78:79], 0
	v_mov_b64_e32 v[80:81], 0
	v_mov_b64_e32 v[82:83], 0
	v_mov_b64_e32 v[84:85], 0
	v_mov_b64_e32 v[86:87], 0
	v_mov_b64_e32 v[88:89], 0
	v_mov_b64_e32 v[90:91], 0
	v_mov_b64_e32 v[92:93], 0
	v_mov_b64_e32 v[94:95], 0
	v_mov_b64_e32 v[96:97], 0
	v_mov_b64_e32 v[98:99], 0
	v_mov_b64_e32 v[100:101], 0
	v_mov_b64_e32 v[102:103], 0
	v_mov_b64_e32 v[104:105], 0
	v_mov_b64_e32 v[106:107], 0
	v_mov_b64_e32 v[108:109], 0
	v_mov_b64_e32 v[110:111], 0
	v_mov_b64_e32 v[112:113], 0
	v_mov_b64_e32 v[114:115], 0
	v_mov_b64_e32 v[116:117], 0
	v_mov_b64_e32 v[118:119], 0
	v_mov_b64_e32 v[120:121], 0
	v_mov_b64_e32 v[122:123], 0
	v_mov_b64_e32 v[124:125], 0
	v_mov_b64_e32 v[126:127], 0
	v_mov_b64_e32 v[128:129], 0
	v_mov_b64_e32 v[130:131], 0
	v_mov_b64_e32 v[132:133], 0
	v_mov_b64_e32 v[134:135], 0
	v_mov_b64_e32 v[136:137], 0
	v_mov_b64_e32 v[138:139], 0
	v_mov_b64_e32 v[140:141], 0
	v_mov_b64_e32 v[142:143], 0
	v_mov_b64_e32 v[144:145], 0
	v_mov_b64_e32 v[146:147], 0
	v_mov_b64_e32 v[148:149], 0
	v_mov_b64_e32 v[150:151], 0
	v_mov_b64_e32 v[152:153], 0
	v_mov_b64_e32 v[154:155], 0
	v_mov_b64_e32 v[156:157], 0
	v_mov_b64_e32 v[158:159], 0
	v_mov_b64_e32 v[160:161], 0
	v_mov_b64_e32 v[162:163], 0
	v_mov_b64_e32 v[164:165], 0
	v_mov_b64_e32 v[166:167], 0
	v_mov_b64_e32 v[168:169], 0
	v_mov_b64_e32 v[170:171], 0
	v_mov_b64_e32 v[172:173], 0
	v_mov_b64_e32 v[174:175], 0
	v_mov_b64_e32 v[176:177], 0
	v_mov_b64_e32 v[178:179], 0
	v_mov_b64_e32 v[180:181], 0
	v_mov_b64_e32 v[182:183], 0
	v_mov_b64_e32 v[184:185], 0
	v_mov_b64_e32 v[186:187], 0
	v_mov_b64_e32 v[188:189], 0
	v_mov_b64_e32 v[190:191], 0
	v_mov_b64_e32 v[192:193], 0
	s_branch .LBB0_1591

.LBB0_2222:
	s_lshl_b32 s24, s61, 11
	s_lshl_b32 s25, s60, 8
	s_add_i32 s24, s25, s24
	s_ashr_i32 s25, s24, 31
	s_lshl_b64 s[24:25], s[24:25], 11
	s_add_u32 s24, s34, s24
	s_addc_u32 s25, s35, s25
	s_and_b64 s[0:1], s[0:1], exec
	s_cselect_b32 s65, s25, s7
	s_cselect_b32 s66, s24, s6
	s_cmp_lg_u32 s26, 0
	s_cselect_b64 s[0:1], -1, 0
	s_add_u32 s67, s6, 0x100
	v_mov_b32_e32 v66, 0
	s_addc_u32 s68, s7, 0
	v_lshl_add_u64 v[210:211], s[4:5], 0, v[202:203]
	v_lshl_add_u64 v[212:213], s[4:5], 0, v[204:205]
	s_mov_b32 s69, -2
	s_mov_b64 s[6:7], 0
	v_mov_b64_e32 v[66:67], 0
	v_mov_b64_e32 v[68:69], 0
	v_mov_b64_e32 v[70:71], 0
	v_mov_b64_e32 v[72:73], 0
	v_mov_b64_e32 v[74:75], 0
	v_mov_b64_e32 v[76:77], 0
	v_mov_b64_e32 v[78:79], 0
	v_mov_b64_e32 v[80:81], 0
	v_mov_b64_e32 v[82:83], 0
	v_mov_b64_e32 v[84:85], 0
	v_mov_b64_e32 v[86:87], 0
	v_mov_b64_e32 v[88:89], 0
	v_mov_b64_e32 v[90:91], 0
	v_mov_b64_e32 v[92:93], 0
	v_mov_b64_e32 v[94:95], 0
	v_mov_b64_e32 v[96:97], 0
	v_mov_b64_e32 v[98:99], 0
	v_mov_b64_e32 v[100:101], 0
	v_mov_b64_e32 v[102:103], 0
	v_mov_b64_e32 v[104:105], 0
	v_mov_b64_e32 v[106:107], 0
	v_mov_b64_e32 v[108:109], 0
	v_mov_b64_e32 v[110:111], 0
	v_mov_b64_e32 v[112:113], 0
	v_mov_b64_e32 v[114:115], 0
	v_mov_b64_e32 v[116:117], 0
	v_mov_b64_e32 v[118:119], 0
	v_mov_b64_e32 v[120:121], 0
	v_mov_b64_e32 v[122:123], 0
	v_mov_b64_e32 v[124:125], 0
	v_mov_b64_e32 v[126:127], 0
	v_mov_b64_e32 v[128:129], 0
	v_mov_b64_e32 v[130:131], 0
	v_mov_b64_e32 v[132:133], 0
	v_mov_b64_e32 v[134:135], 0
	v_mov_b64_e32 v[136:137], 0
	v_mov_b64_e32 v[138:139], 0
	v_mov_b64_e32 v[140:141], 0
	v_mov_b64_e32 v[142:143], 0
	v_mov_b64_e32 v[144:145], 0
	v_mov_b64_e32 v[146:147], 0
	v_mov_b64_e32 v[148:149], 0
	v_mov_b64_e32 v[150:151], 0
	v_mov_b64_e32 v[152:153], 0
	v_mov_b64_e32 v[154:155], 0
	v_mov_b64_e32 v[156:157], 0
	v_mov_b64_e32 v[158:159], 0
	v_mov_b64_e32 v[160:161], 0
	v_mov_b64_e32 v[162:163], 0
	v_mov_b64_e32 v[164:165], 0
	v_mov_b64_e32 v[166:167], 0
	v_mov_b64_e32 v[168:169], 0
	v_mov_b64_e32 v[170:171], 0
	v_mov_b64_e32 v[172:173], 0
	v_mov_b64_e32 v[174:175], 0
	v_mov_b64_e32 v[176:177], 0
	v_mov_b64_e32 v[178:179], 0
	v_mov_b64_e32 v[180:181], 0
	v_mov_b64_e32 v[182:183], 0
	v_mov_b64_e32 v[184:185], 0
	v_mov_b64_e32 v[186:187], 0
	v_mov_b64_e32 v[188:189], 0
	v_mov_b64_e32 v[190:191], 0
	v_mov_b64_e32 v[192:193], 0
	s_branch .LBB0_2225

.LBB0_2407:
	s_ashr_i32 s21, s20, 31
	s_lshl_b64 s[24:25], s[20:21], 19
	s_add_u32 s24, s46, s24
	s_addc_u32 s25, s47, s25
	s_and_b64 s[26:27], s[2:3], exec
	s_cselect_b32 s21, s25, s31
	s_cselect_b32 s72, s24, s30
	s_ashr_i32 s23, s22, 31
	s_lshl_b64 s[26:27], s[22:23], 19
	s_add_u32 s26, s48, s26
	s_addc_u32 s27, s49, s27
	s_and_b64 s[38:39], s[2:3], exec
	s_cselect_b32 s23, s27, s37
	s_cselect_b32 s73, s26, s36
	s_cmp_lg_u32 s34, 0
	s_cselect_b64 s[34:35], -1, 0
	s_add_u32 s74, s36, 0x100
	v_mov_b32_e32 v66, 0
	s_addc_u32 s75, s37, 0
	v_lshl_add_u64 v[210:211], s[30:31], 0, v[202:203]
	v_lshl_add_u64 v[212:213], s[30:31], 0, v[204:205]
	s_mov_b32 s76, -2
	s_mov_b64 s[36:37], 0
	v_mov_b64_e32 v[66:67], 0
	v_mov_b64_e32 v[68:69], 0
	v_mov_b64_e32 v[70:71], 0
	v_mov_b64_e32 v[72:73], 0
	v_mov_b64_e32 v[74:75], 0
	v_mov_b64_e32 v[76:77], 0
	v_mov_b64_e32 v[78:79], 0
	v_mov_b64_e32 v[80:81], 0
	v_mov_b64_e32 v[82:83], 0
	v_mov_b64_e32 v[84:85], 0
	v_mov_b64_e32 v[86:87], 0
	v_mov_b64_e32 v[88:89], 0
	v_mov_b64_e32 v[90:91], 0
	v_mov_b64_e32 v[92:93], 0
	v_mov_b64_e32 v[94:95], 0
	v_mov_b64_e32 v[96:97], 0
	v_mov_b64_e32 v[98:99], 0
	v_mov_b64_e32 v[100:101], 0
	v_mov_b64_e32 v[102:103], 0
	v_mov_b64_e32 v[104:105], 0
	v_mov_b64_e32 v[106:107], 0
	v_mov_b64_e32 v[108:109], 0
	v_mov_b64_e32 v[110:111], 0
	v_mov_b64_e32 v[112:113], 0
	v_mov_b64_e32 v[114:115], 0
	v_mov_b64_e32 v[116:117], 0
	v_mov_b64_e32 v[118:119], 0
	v_mov_b64_e32 v[120:121], 0
	v_mov_b64_e32 v[122:123], 0
	v_mov_b64_e32 v[124:125], 0
	v_mov_b64_e32 v[126:127], 0
	v_mov_b64_e32 v[128:129], 0
	v_mov_b64_e32 v[130:131], 0
	v_mov_b64_e32 v[132:133], 0
	v_mov_b64_e32 v[134:135], 0
	v_mov_b64_e32 v[136:137], 0
	v_mov_b64_e32 v[138:139], 0
	v_mov_b64_e32 v[140:141], 0
	v_mov_b64_e32 v[142:143], 0
	v_mov_b64_e32 v[144:145], 0
	v_mov_b64_e32 v[146:147], 0
	v_mov_b64_e32 v[148:149], 0
	v_mov_b64_e32 v[150:151], 0
	v_mov_b64_e32 v[152:153], 0
	v_mov_b64_e32 v[154:155], 0
	v_mov_b64_e32 v[156:157], 0
	v_mov_b64_e32 v[158:159], 0
	v_mov_b64_e32 v[160:161], 0
	v_mov_b64_e32 v[162:163], 0
	v_mov_b64_e32 v[164:165], 0
	v_mov_b64_e32 v[166:167], 0
	v_mov_b64_e32 v[168:169], 0
	v_mov_b64_e32 v[170:171], 0
	v_mov_b64_e32 v[172:173], 0
	v_mov_b64_e32 v[174:175], 0
	v_mov_b64_e32 v[176:177], 0
	v_mov_b64_e32 v[178:179], 0
	v_mov_b64_e32 v[180:181], 0
	v_mov_b64_e32 v[182:183], 0
	v_mov_b64_e32 v[184:185], 0
	v_mov_b64_e32 v[186:187], 0
	v_mov_b64_e32 v[188:189], 0
	v_mov_b64_e32 v[190:191], 0
	v_mov_b64_e32 v[192:193], 0
	s_branch .LBB0_2410

.LBB0_2739:
	s_cmp_lg_u32 s24, 0
	s_cselect_b64 s[24:25], -1, 0
	s_add_u32 s67, s26, 0x100
	v_mov_b32_e32 v2, 0
	s_addc_u32 s68, s27, 0
	v_lshl_add_u64 v[210:211], s[22:23], 0, v[202:203]
	v_lshl_add_u64 v[212:213], s[22:23], 0, v[204:205]
	s_mov_b32 s69, -2
	s_mov_b64 s[26:27], 0
	v_mov_b64_e32 v[2:3], 0
	v_mov_b64_e32 v[4:5], 0
	v_mov_b64_e32 v[6:7], 0
	v_mov_b64_e32 v[8:9], 0
	v_mov_b64_e32 v[10:11], 0
	v_mov_b64_e32 v[12:13], 0
	v_mov_b64_e32 v[14:15], 0
	v_mov_b64_e32 v[16:17], 0
	v_mov_b64_e32 v[18:19], 0
	v_mov_b64_e32 v[20:21], 0
	v_mov_b64_e32 v[22:23], 0
	v_mov_b64_e32 v[24:25], 0
	v_mov_b64_e32 v[26:27], 0
	v_mov_b64_e32 v[28:29], 0
	v_mov_b64_e32 v[30:31], 0
	v_mov_b64_e32 v[32:33], 0
	v_mov_b64_e32 v[34:35], 0
	v_mov_b64_e32 v[36:37], 0
	v_mov_b64_e32 v[38:39], 0
	v_mov_b64_e32 v[40:41], 0
	v_mov_b64_e32 v[42:43], 0
	v_mov_b64_e32 v[44:45], 0
	v_mov_b64_e32 v[46:47], 0
	v_mov_b64_e32 v[48:49], 0
	v_mov_b64_e32 v[50:51], 0
	v_mov_b64_e32 v[52:53], 0
	v_mov_b64_e32 v[54:55], 0
	v_mov_b64_e32 v[56:57], 0
	v_mov_b64_e32 v[58:59], 0
	v_mov_b64_e32 v[60:61], 0
	v_mov_b64_e32 v[62:63], 0
	v_mov_b64_e32 v[64:65], 0
	v_mov_b64_e32 v[66:67], 0
	v_mov_b64_e32 v[68:69], 0
	v_mov_b64_e32 v[70:71], 0
	v_mov_b64_e32 v[72:73], 0
	v_mov_b64_e32 v[74:75], 0
	v_mov_b64_e32 v[76:77], 0
	v_mov_b64_e32 v[78:79], 0
	v_mov_b64_e32 v[80:81], 0
	v_mov_b64_e32 v[82:83], 0
	v_mov_b64_e32 v[84:85], 0
	v_mov_b64_e32 v[86:87], 0
	v_mov_b64_e32 v[88:89], 0
	v_mov_b64_e32 v[90:91], 0
	v_mov_b64_e32 v[92:93], 0
	v_mov_b64_e32 v[94:95], 0
	v_mov_b64_e32 v[96:97], 0
	v_mov_b64_e32 v[98:99], 0
	v_mov_b64_e32 v[100:101], 0
	v_mov_b64_e32 v[102:103], 0
	v_mov_b64_e32 v[104:105], 0
	v_mov_b64_e32 v[106:107], 0
	v_mov_b64_e32 v[108:109], 0
	v_mov_b64_e32 v[110:111], 0
	v_mov_b64_e32 v[112:113], 0
	v_mov_b64_e32 v[114:115], 0
	v_mov_b64_e32 v[116:117], 0
	v_mov_b64_e32 v[118:119], 0
	v_mov_b64_e32 v[120:121], 0
	v_mov_b64_e32 v[122:123], 0
	v_mov_b64_e32 v[124:125], 0
	v_mov_b64_e32 v[126:127], 0
	v_mov_b64_e32 v[128:129], 0
	s_branch .LBB0_2742
